# P1 in-proj epilogue: lane exchanges pipelined through LDS (counted lgkmcnt), stores trail 3 groups
# speedup vs baseline: 1.0461x; 1.0018x over previous
; #define PG8_LAS __attribute__((address_space(3)))
; __device__ __forceinline__ unsigned cvt_pk_bf16(float lo, float hi) { unsigned r; asm volatile("v_cvt_pk_bf16_f32 %0, %1, %2" : "=v"(r) : "v"(lo), "v"(hi)); return r; }
;     __device__ __forceinline__ void operator()(const f32x4 (&acc)[2][2][4][2], const Unit& u_, int wr, int wc, int fr, int fq) const {
;     ...
;         const int l = fq * 16 + fr; PG8_LAS unsigned char* xl = xl0 + (wr * 4 + wc) * XCHG_WAVE_BYTES;
;         const int rowb = u.pm * BM + wr * 64 + (l >> 2); const int colb = colt + wc * 32 + 8 * (l & 3);
; #pragma unroll
;         for (int ai = 0; ai < 2; ++ai)
; #pragma unroll
;             for (int m = 0; m < 4; ++m) { bf16_t* rowp = base + (size_t)(rowb + ai * HALF + m * 16) * ldc + colb;
; #pragma unroll
;                 for (int bj = 0; bj < 2; ++bj) { const f32x4 v0 = acc[ai][bj][m][0], v1 = acc[ai][bj][m][1];
;                     u32x4 w; w.x = cvt_pk_bf16(v0[0], v0[1]); w.y = cvt_pk_bf16(v0[2], v0[3]); w.z = cvt_pk_bf16(v1[0], v1[1]); w.w = cvt_pk_bf16(v1[2], v1[3]);
;                     *(u32x4*)(rowp + bj * HALF) = xchg_bf16(xl, fr, fq, l, w); } }
.LBB0_263:
	v_lshl_add_u32 v161, s43, 8, v157
	v_add_u32_e32 v152, s2, v156
	v_ashrrev_i32_e32 v153, 31, v152
	v_lshl_add_u64 v[152:153], v[152:153], 1, s[58:59]
	v_mad_u64_u32 v[210:211], s[12:13], s56, v161, 0
	v_lshl_add_u64 v[210:211], v[210:211], 1, v[152:153]
	v_add_u32_e32 v226, 0x10, v161
	v_mad_u64_u32 v[212:213], s[12:13], s56, v226, 0
	v_lshl_add_u64 v[212:213], v[212:213], 1, v[152:153]
	v_add_u32_e32 v226, 0x20, v161
	v_mad_u64_u32 v[214:215], s[12:13], s56, v226, 0
	v_lshl_add_u64 v[214:215], v[214:215], 1, v[152:153]
	v_add_u32_e32 v226, 0x30, v161
	v_mad_u64_u32 v[216:217], s[12:13], s56, v226, 0
	v_lshl_add_u64 v[216:217], v[216:217], 1, v[152:153]
	v_add_u32_e32 v226, 0x80, v161
	v_mad_u64_u32 v[218:219], s[12:13], s56, v226, 0
	v_lshl_add_u64 v[218:219], v[218:219], 1, v[152:153]
	v_add_u32_e32 v226, 0x90, v161
	v_mad_u64_u32 v[220:221], s[12:13], s56, v226, 0
	v_lshl_add_u64 v[220:221], v[220:221], 1, v[152:153]
	v_add_u32_e32 v226, 0xa0, v161
	v_mad_u64_u32 v[222:223], s[12:13], s56, v226, 0
	v_lshl_add_u64 v[222:223], v[222:223], 1, v[152:153]
	v_add_u32_e32 v226, 0xb0, v161
	v_mad_u64_u32 v[224:225], s[12:13], s56, v226, 0
	v_lshl_add_u64 v[224:225], v[224:225], 1, v[152:153]
	s_andn2_b64 vcc, exec, s[0:1]
	s_mov_b64 s[0:1], -1
	v_cvt_pk_bf16_f32 v226, v126, v127
	v_cvt_pk_bf16_f32 v227, v128, v129
	v_cvt_pk_bf16_f32 v228, v122, v123
	v_cvt_pk_bf16_f32 v229, v124, v125
	ds_write_b128 v159, v[226:229]
	ds_read_b128 v[162:165], v160
	v_cvt_pk_bf16_f32 v230, v118, v119
	v_cvt_pk_bf16_f32 v231, v120, v121
	v_cvt_pk_bf16_f32 v232, v110, v111
	v_cvt_pk_bf16_f32 v233, v112, v113
	ds_write_b128 v159, v[230:233]
	ds_read_b128 v[166:169], v160
	v_cvt_pk_bf16_f32 v226, v114, v115
	v_cvt_pk_bf16_f32 v227, v116, v117
	v_cvt_pk_bf16_f32 v228, v106, v107
	v_cvt_pk_bf16_f32 v229, v108, v109
	ds_write_b128 v159, v[226:229]
	ds_read_b128 v[170:173], v160
	v_cvt_pk_bf16_f32 v230, v102, v103
	v_cvt_pk_bf16_f32 v231, v104, v105
	v_cvt_pk_bf16_f32 v232, v94, v95
	v_cvt_pk_bf16_f32 v233, v96, v97
	ds_write_b128 v159, v[230:233]
	ds_read_b128 v[174:177], v160
	s_waitcnt lgkmcnt(6)
	global_store_dwordx4 v[210:211], v[162:165], off nt
	v_cvt_pk_bf16_f32 v226, v98, v99
	v_cvt_pk_bf16_f32 v227, v100, v101
	v_cvt_pk_bf16_f32 v228, v90, v91
	v_cvt_pk_bf16_f32 v229, v92, v93
	ds_write_b128 v159, v[226:229]
	ds_read_b128 v[178:181], v160
	s_waitcnt lgkmcnt(6)
	global_store_dwordx4 v[210:211], v[166:169], off offset:256 nt
	v_cvt_pk_bf16_f32 v230, v86, v87
	v_cvt_pk_bf16_f32 v231, v88, v89
	v_cvt_pk_bf16_f32 v232, v78, v79
	v_cvt_pk_bf16_f32 v233, v80, v81
	ds_write_b128 v159, v[230:233]
	ds_read_b128 v[182:185], v160
	s_waitcnt lgkmcnt(6)
	global_store_dwordx4 v[212:213], v[170:173], off nt
	v_cvt_pk_bf16_f32 v226, v82, v83
	v_cvt_pk_bf16_f32 v227, v84, v85
	v_cvt_pk_bf16_f32 v228, v74, v75
	v_cvt_pk_bf16_f32 v229, v76, v77
	ds_write_b128 v159, v[226:229]
	ds_read_b128 v[186:189], v160
	s_waitcnt lgkmcnt(6)
	global_store_dwordx4 v[212:213], v[174:177], off offset:256 nt
	v_cvt_pk_bf16_f32 v230, v70, v71
	v_cvt_pk_bf16_f32 v231, v72, v73
	v_cvt_pk_bf16_f32 v232, v66, v67
	v_cvt_pk_bf16_f32 v233, v68, v69
	ds_write_b128 v159, v[230:233]
	ds_read_b128 v[190:193], v160
	s_waitcnt lgkmcnt(6)
	global_store_dwordx4 v[214:215], v[178:181], off nt
	v_cvt_pk_bf16_f32 v226, v62, v63
	v_cvt_pk_bf16_f32 v227, v64, v65
	v_cvt_pk_bf16_f32 v228, v58, v59
	v_cvt_pk_bf16_f32 v229, v60, v61
	ds_write_b128 v159, v[226:229]
	ds_read_b128 v[194:197], v160
	s_waitcnt lgkmcnt(6)
	global_store_dwordx4 v[214:215], v[182:185], off offset:256 nt
	v_cvt_pk_bf16_f32 v230, v54, v55
	v_cvt_pk_bf16_f32 v231, v56, v57
	v_cvt_pk_bf16_f32 v232, v46, v47
	v_cvt_pk_bf16_f32 v233, v48, v49
	ds_write_b128 v159, v[230:233]
	ds_read_b128 v[198:201], v160
	s_waitcnt lgkmcnt(6)
	global_store_dwordx4 v[216:217], v[186:189], off nt
	v_cvt_pk_bf16_f32 v226, v50, v51
	v_cvt_pk_bf16_f32 v227, v52, v53
	v_cvt_pk_bf16_f32 v228, v42, v43
	v_cvt_pk_bf16_f32 v229, v44, v45
	ds_write_b128 v159, v[226:229]
	ds_read_b128 v[202:205], v160
	s_waitcnt lgkmcnt(6)
	global_store_dwordx4 v[216:217], v[190:193], off offset:256 nt
	v_cvt_pk_bf16_f32 v230, v38, v39
	v_cvt_pk_bf16_f32 v231, v40, v41
	v_cvt_pk_bf16_f32 v232, v30, v31
	v_cvt_pk_bf16_f32 v233, v32, v33
	ds_write_b128 v159, v[230:233]
	ds_read_b128 v[206:209], v160
	s_waitcnt lgkmcnt(6)
	global_store_dwordx4 v[218:219], v[194:197], off nt
	v_cvt_pk_bf16_f32 v226, v34, v35
	v_cvt_pk_bf16_f32 v227, v36, v37
	v_cvt_pk_bf16_f32 v228, v26, v27
	v_cvt_pk_bf16_f32 v229, v28, v29
	ds_write_b128 v159, v[226:229]
	ds_read_b128 v[162:165], v160
	s_waitcnt lgkmcnt(6)
	global_store_dwordx4 v[218:219], v[198:201], off offset:256 nt
	v_cvt_pk_bf16_f32 v230, v22, v23
	v_cvt_pk_bf16_f32 v231, v24, v25
	v_cvt_pk_bf16_f32 v232, v14, v15
	v_cvt_pk_bf16_f32 v233, v16, v17
	ds_write_b128 v159, v[230:233]
	ds_read_b128 v[166:169], v160
	s_waitcnt lgkmcnt(6)
	global_store_dwordx4 v[220:221], v[202:205], off nt
	v_cvt_pk_bf16_f32 v226, v18, v19
	v_cvt_pk_bf16_f32 v227, v20, v21
	v_cvt_pk_bf16_f32 v228, v10, v11
	v_cvt_pk_bf16_f32 v229, v12, v13
	ds_write_b128 v159, v[226:229]
	ds_read_b128 v[170:173], v160
	s_waitcnt lgkmcnt(6)
	global_store_dwordx4 v[220:221], v[206:209], off offset:256 nt
	v_cvt_pk_bf16_f32 v230, v6, v7
	v_cvt_pk_bf16_f32 v231, v8, v9
	v_cvt_pk_bf16_f32 v232, v2, v3
	v_cvt_pk_bf16_f32 v233, v4, v5
	ds_write_b128 v159, v[230:233]
	ds_read_b128 v[174:177], v160
	s_waitcnt lgkmcnt(6)
	global_store_dwordx4 v[222:223], v[162:165], off nt
	s_waitcnt lgkmcnt(4)
	global_store_dwordx4 v[222:223], v[166:169], off offset:256 nt
	s_waitcnt lgkmcnt(2)
	global_store_dwordx4 v[224:225], v[170:173], off nt
	s_waitcnt lgkmcnt(0)
	global_store_dwordx4 v[224:225], v[174:177], off offset:256 nt
	s_cbranch_vccnz .LBB0_244
	s_andn2_b64 vcc, exec, s[4:5]
	s_cbranch_vccnz .LBB0_243
	s_barrier
	s_branch .LBB0_243
